# P1: hoisted per-chunk g/shift/scale loads with counted waits (on top of P7/P11/P6/P8/P12/P2 epilogue work)
# speedup vs baseline: 1.0456x; 1.0064x over previous
; __global__ void __launch_bounds__(NTHR, 2) fwd_kernel(Args a) {
;     ...
;     for (int m = gw; m < MT; m += NGW) {
;         const float* src = m < M ? a.in[I_X] + (size_t)m * DM : a.in[I_CTX] + (size_t)(m - M) * DM;
;         const float* md = mod + (m < M ? (m >> 11) : 4) * MODW;
;         f32x4 v[8]; float ss = 0.f;
; #pragma unroll
;         for (int j = 0; j < 8; ++j) { v[j] = *(const f32x4*)(src + j * 256 + lane * 4); ss += (v[j][0] * v[j][0] + v[j][1] * v[j][1]) + (v[j][2] * v[j][2] + v[j][3] * v[j][3]); }
;         const float rstd = rsqrtf(wave_sum(ss) * (1.0f / DM) + EPS);
.LBB0_163:
	global_load_dwordx4 v[48:51], v20, s[14:15]
	global_load_dwordx4 v[52:55], v20, s[14:15] offset:1024
	global_load_dwordx4 v[56:59], v20, s[14:15] offset:2048
	global_load_dwordx4 v[16:19], v20, s[14:15] offset:3072
	v_lshl_add_u64 v[0:1], s[14:15], 0, v[20:21]
	v_add_co_u32_e32 v4, vcc, s20, v0
	s_min_i32 s0, s2, 0x2000
	s_nop 0
	v_addc_co_u32_e32 v5, vcc, 0, v1, vcc
	global_load_dwordx4 v[8:11], v[4:5], off
	global_load_dwordx4 v[12:15], v[4:5], off offset:1024
	global_load_dwordx4 v[0:3], v[4:5], off offset:3072
	s_nop 0
	global_load_dwordx4 v[4:7], v[4:5], off offset:2048
	s_lshr_b32 s0, s0, 11
	s_mul_i32 s14, s0, 0x3000
	s_ashr_i32 s15, s14, 31
	s_lshl_b64 s[14:15], s[14:15], 2
	s_add_u32 s14, s68, s14
	s_addc_u32 s15, s69, s15
	s_add_u32 s16, s14, 0x2000
	global_load_dwordx4 v[60:63], v[22:23], off
	s_addc_u32 s17, s15, 0
	global_load_dwordx4 v[64:67], v20, s[14:15]
	global_load_dwordx4 v[68:71], v20, s[16:17]
	global_load_dwordx4 v[96:99], v[22:23], off offset:1024
	global_load_dwordx4 v[100:103], v41, s[16:17]
	global_load_dwordx4 v[104:107], v20, s[14:15] offset:1024
	global_load_dwordx4 v[108:111], v[22:23], off offset:2048
	global_load_dwordx4 v[112:115], v42, s[16:17]
	global_load_dwordx4 v[116:119], v20, s[14:15] offset:2048
	global_load_dwordx4 v[120:123], v[22:23], off offset:3072
	global_load_dwordx4 v[124:127], v43, s[16:17]
	global_load_dwordx4 v[128:131], v20, s[14:15] offset:3072
	global_load_dwordx4 v[132:135], v[24:25], off
	global_load_dwordx4 v[136:139], v44, s[16:17]
	global_load_dwordx4 v[140:143], v44, s[14:15]
	global_load_dwordx4 v[144:147], v[26:27], off
	global_load_dwordx4 v[148:151], v45, s[16:17]
	global_load_dwordx4 v[152:155], v45, s[14:15]
	global_load_dwordx4 v[156:159], v[28:29], off
	global_load_dwordx4 v[160:163], v46, s[16:17]
	global_load_dwordx4 v[164:167], v46, s[14:15]
	global_load_dwordx4 v[168:171], v[30:31], off
	global_load_dwordx4 v[172:175], v47, s[16:17]
	global_load_dwordx4 v[176:179], v47, s[14:15]
	s_lshl_b64 s[18:19], s[18:19], 12
	s_add_u32 s2, s2, s70
	s_addc_u32 s3, s3, s71
	s_add_u32 s4, s4, s12
	s_addc_u32 s5, s5, s13
	s_cmpk_gt_i32 s2, 0x23ff
	s_waitcnt vmcnt(31)
	v_mov_b32_e32 v74, v49
	s_waitcnt vmcnt(30)
	v_mov_b32_e32 v75, v53
	v_mov_b32_e32 v78, v51
	v_mov_b32_e32 v79, v55
	v_mov_b32_e32 v72, v48
	v_mov_b32_e32 v73, v52
	v_mov_b32_e32 v76, v50
	v_mov_b32_e32 v77, v54
	s_waitcnt vmcnt(29)
	v_pk_mul_f32 v[80:81], v[58:59], v[58:59]
	v_pk_mul_f32 v[82:83], v[56:57], v[56:57]
	v_pk_mul_f32 v[74:75], v[74:75], v[74:75]
	v_pk_mul_f32 v[78:79], v[78:79], v[78:79]
	v_pk_mov_b32 v[88:89], v[82:83], v[80:81] op_sel:[1,0]
	v_mov_b32_e32 v83, v81
	v_pk_fma_f32 v[72:73], v[72:73], v[72:73], v[74:75]
	v_pk_fma_f32 v[74:75], v[76:77], v[76:77], v[78:79]
	s_waitcnt vmcnt(28)
	v_mul_f32_e32 v84, v17, v17
	v_mul_f32_e32 v86, v19, v19
	v_pk_add_f32 v[76:77], v[88:89], v[82:83]
	v_pk_add_f32 v[72:73], v[72:73], v[74:75]
	v_pk_fma_f32 v[80:81], v[16:17], v[16:17], v[84:85] op_sel_hi:[1,1,0]
	v_pk_fma_f32 v[84:85], v[18:19], v[18:19], v[86:87] op_sel_hi:[1,1,0]
	s_waitcnt vmcnt(27)
	v_mul_f32_e32 v89, v8, v8
	v_mul_f32_e32 v90, v9, v9
	v_pk_add_f32 v[74:75], v[76:77], v[76:77] op_sel:[0,1] op_sel_hi:[1,0]
	v_pk_add_f32 v[72:73], v[72:73], v[72:73] op_sel:[0,1] op_sel_hi:[1,0]
	v_mul_f32_e32 v81, v10, v10
	v_mul_f32_e32 v85, v11, v11
	s_waitcnt vmcnt(26)
	v_pk_mul_f32 v[78:79], v[14:15], v[14:15]
	v_pk_mul_f32 v[82:83], v[12:13], v[12:13]
	v_mov_b32_e32 v75, v90
	v_mov_b32_e32 v73, v89
	v_pk_mov_b32 v[76:77], v[82:83], v[78:79] op_sel:[1,0]
	v_mov_b32_e32 v83, v79
	v_pk_add_f32 v[80:81], v[80:81], v[84:85]
	v_pk_add_f32 v[72:73], v[72:73], v[74:75]
	s_waitcnt vmcnt(24)
	v_mul_f32_e32 v86, v5, v5
	v_mul_f32_e32 v88, v7, v7
	v_pk_add_f32 v[76:77], v[76:77], v[82:83]
	v_pk_add_f32 v[72:73], v[72:73], v[80:81]
	v_mul_f32_e32 v91, v0, v0
	v_mul_f32_e32 v92, v1, v1
	v_mul_f32_e32 v93, v2, v2
	v_mul_f32_e32 v94, v3, v3
	v_pk_fma_f32 v[78:79], v[4:5], v[4:5], v[86:87] op_sel_hi:[1,1,0]
	v_pk_fma_f32 v[86:87], v[6:7], v[6:7], v[88:89] op_sel_hi:[1,1,0]
	v_pk_add_f32 v[76:77], v[76:77], v[76:77] op_sel:[0,1] op_sel_hi:[1,0]
	v_pk_add_f32 v[72:73], v[72:73], v[72:73] op_sel:[0,1] op_sel_hi:[1,0]
	v_mov_b32_e32 v79, v93
	v_mov_b32_e32 v87, v94
	v_mov_b32_e32 v77, v92
	v_mov_b32_e32 v73, v91
	v_pk_add_f32 v[78:79], v[78:79], v[86:87]
	v_pk_add_f32 v[72:73], v[72:73], v[76:77]
	s_waitcnt vmcnt(21)
	v_pk_add_f32 v[70:71], v[70:71], 1.0 op_sel_hi:[1,0]
	v_pk_add_f32 v[72:73], v[72:73], v[78:79]
	v_pk_add_f32 v[68:69], v[68:69], 1.0 op_sel_hi:[1,0]
	v_add_f32_e32 v72, v72, v73
	ds_bpermute_b32 v73, v34, v72
	s_waitcnt lgkmcnt(0)
	v_add_f32_e32 v72, v72, v73
	ds_bpermute_b32 v73, v35, v72
	s_waitcnt lgkmcnt(0)
	v_add_f32_e32 v72, v72, v73
	ds_bpermute_b32 v73, v36, v72
	s_waitcnt lgkmcnt(0)
	v_add_f32_e32 v72, v72, v73
	ds_bpermute_b32 v73, v37, v72
	s_waitcnt lgkmcnt(0)
	v_add_f32_e32 v72, v72, v73
	ds_bpermute_b32 v73, v38, v72
	s_waitcnt lgkmcnt(0)
	v_add_f32_e32 v72, v72, v73
	ds_bpermute_b32 v73, v39, v72
	s_waitcnt lgkmcnt(0)
; __device__ __forceinline__ void st_bf4(bf16_t* p, f32x4 v) { u32x2 w; w.x = pk2(v[0], v[1]); w.y = pk2(v[2], v[3]); *(u32x2*)p = w; }
; __global__ void __launch_bounds__(NTHR, 2) fwd_kernel(Args a) {
;     ...
;         const float rstd = rsqrtf(wave_sum(ss) * (1.0f / DM) + EPS);
; #pragma unroll
;         for (int j = 0; j < 8; ++j) { const int c = j * 256 + lane * 4;
;             const f32x4 g = *(const f32x4*)(a.in[I_G1] + c), sh = *(const f32x4*)(md + c), sc = *(const f32x4*)(md + DM + c);
;             st_bf4(H1 + (size_t)m * DM + c, (v[j] * rstd * g) * (sc + 1.0f) + sh); }
	v_add_f32_e32 v72, v72, v73
	v_fmamk_f32 v72, v72, 0x3a000000, v40
	v_mul_f32_e32 v73, 0x4b800000, v72
	v_cmp_gt_f32_e32 vcc, s21, v72
	s_nop 1
	v_cndmask_b32_e32 v72, v72, v73, vcc
	v_rsq_f32_e32 v74, v72
	v_lshl_add_u64 v[72:73], v[32:33], 0, s[18:19]
	v_mul_f32_e32 v75, 0x45800000, v74
	v_cndmask_b32_e32 v74, v74, v75, vcc
	v_pk_mul_f32 v[50:51], v[74:75], v[50:51] op_sel_hi:[0,1]
	v_pk_mul_f32 v[48:49], v[74:75], v[48:49] op_sel_hi:[0,1]
	v_pk_mul_f32 v[48:49], v[60:61], v[48:49]
	v_pk_mul_f32 v[50:51], v[62:63], v[50:51]
	v_pk_fma_f32 v[48:49], v[68:69], v[48:49], v[64:65]
	v_pk_fma_f32 v[50:51], v[70:71], v[50:51], v[66:67]
	v_cvt_pk_bf16_f32 v48, v48, v49
	v_cvt_pk_bf16_f32 v49, v50, v51
	global_store_dwordx2 v[72:73], v[48:49], off
	s_nop 0
	v_pk_mul_f32 v[54:55], v[74:75], v[54:55] op_sel_hi:[0,1]
	v_pk_mul_f32 v[52:53], v[74:75], v[52:53] op_sel_hi:[0,1]
	v_pk_mul_f32 v[58:59], v[74:75], v[58:59] op_sel_hi:[0,1]
	v_pk_mul_f32 v[56:57], v[74:75], v[56:57] op_sel_hi:[0,1]
	v_pk_mul_f32 v[18:19], v[74:75], v[18:19] op_sel_hi:[0,1]
	v_pk_mul_f32 v[16:17], v[74:75], v[16:17] op_sel_hi:[0,1]
	v_pk_mul_f32 v[10:11], v[74:75], v[10:11] op_sel_hi:[0,1]
	v_pk_mul_f32 v[8:9], v[74:75], v[8:9] op_sel_hi:[0,1]
	v_pk_mul_f32 v[14:15], v[74:75], v[14:15] op_sel_hi:[0,1]
	v_pk_mul_f32 v[12:13], v[74:75], v[12:13] op_sel_hi:[0,1]
	v_pk_mul_f32 v[6:7], v[74:75], v[6:7] op_sel_hi:[0,1]
	v_pk_mul_f32 v[4:5], v[74:75], v[4:5] op_sel_hi:[0,1]
	v_pk_mul_f32 v[2:3], v[74:75], v[2:3] op_sel_hi:[0,1]
	v_pk_mul_f32 v[0:1], v[74:75], v[0:1] op_sel_hi:[0,1]
	s_waitcnt vmcnt(21)
	v_pk_mul_f32 v[48:49], v[96:97], v[52:53]
	v_pk_mul_f32 v[50:51], v[98:99], v[54:55]
	s_waitcnt vmcnt(20)
	v_pk_add_f32 v[52:53], v[102:103], 1.0 op_sel_hi:[1,0]
	v_pk_add_f32 v[54:55], v[100:101], 1.0 op_sel_hi:[1,0]
	s_waitcnt vmcnt(19)
	v_pk_fma_f32 v[50:51], v[52:53], v[50:51], v[106:107]
	v_pk_fma_f32 v[48:49], v[54:55], v[48:49], v[104:105]
	s_nop 0
	v_cvt_pk_bf16_f32 v48, v48, v49
	v_cvt_pk_bf16_f32 v49, v50, v51
	global_store_dwordx2 v[72:73], v[48:49], off offset:512
	s_nop 0
	s_waitcnt vmcnt(19)
	v_pk_mul_f32 v[48:49], v[108:109], v[56:57]
	v_pk_mul_f32 v[50:51], v[110:111], v[58:59]
	s_waitcnt vmcnt(18)
	v_pk_add_f32 v[54:55], v[114:115], 1.0 op_sel_hi:[1,0]
	v_pk_add_f32 v[52:53], v[112:113], 1.0 op_sel_hi:[1,0]
	s_waitcnt vmcnt(17)
	v_pk_fma_f32 v[50:51], v[54:55], v[50:51], v[118:119]
	v_pk_fma_f32 v[48:49], v[52:53], v[48:49], v[116:117]
	s_nop 0
	v_cvt_pk_bf16_f32 v48, v48, v49
	v_cvt_pk_bf16_f32 v49, v50, v51
	global_store_dwordx2 v[72:73], v[48:49], off offset:1024
	s_nop 0
	s_waitcnt vmcnt(17)
	v_pk_mul_f32 v[16:17], v[120:121], v[16:17]
	v_pk_mul_f32 v[18:19], v[122:123], v[18:19]
	s_waitcnt vmcnt(16)
	v_pk_add_f32 v[48:49], v[126:127], 1.0 op_sel_hi:[1,0]
	v_pk_add_f32 v[50:51], v[124:125], 1.0 op_sel_hi:[1,0]
	s_waitcnt vmcnt(15)
	v_pk_fma_f32 v[18:19], v[48:49], v[18:19], v[130:131]
	v_pk_fma_f32 v[16:17], v[50:51], v[16:17], v[128:129]
	s_nop 0
	v_cvt_pk_bf16_f32 v16, v16, v17
	v_cvt_pk_bf16_f32 v17, v18, v19
	global_store_dwordx2 v[72:73], v[16:17], off offset:1536
	s_nop 0
	s_waitcnt vmcnt(15)
	v_pk_mul_f32 v[8:9], v[132:133], v[8:9]
	v_pk_mul_f32 v[10:11], v[134:135], v[10:11]
	s_waitcnt vmcnt(14)
	v_pk_add_f32 v[16:17], v[138:139], 1.0 op_sel_hi:[1,0]
	v_pk_add_f32 v[18:19], v[136:137], 1.0 op_sel_hi:[1,0]
	s_waitcnt vmcnt(13)
	v_pk_fma_f32 v[10:11], v[16:17], v[10:11], v[142:143]
	v_pk_fma_f32 v[8:9], v[18:19], v[8:9], v[140:141]
	s_nop 0
	v_cvt_pk_bf16_f32 v8, v8, v9
	v_cvt_pk_bf16_f32 v9, v10, v11
	global_store_dwordx2 v[72:73], v[8:9], off offset:2048
	s_nop 0
	s_waitcnt vmcnt(13)
	v_pk_mul_f32 v[8:9], v[144:145], v[12:13]
	v_pk_mul_f32 v[10:11], v[146:147], v[14:15]
	s_waitcnt vmcnt(12)
	v_pk_add_f32 v[12:13], v[150:151], 1.0 op_sel_hi:[1,0]
	v_pk_add_f32 v[14:15], v[148:149], 1.0 op_sel_hi:[1,0]
	s_waitcnt vmcnt(11)
	v_pk_fma_f32 v[10:11], v[12:13], v[10:11], v[154:155]
	v_pk_fma_f32 v[8:9], v[14:15], v[8:9], v[152:153]
	s_nop 0
	v_cvt_pk_bf16_f32 v8, v8, v9
	v_cvt_pk_bf16_f32 v9, v10, v11
	global_store_dwordx2 v[72:73], v[8:9], off offset:2560
	s_nop 0
	s_waitcnt vmcnt(11)
	v_pk_mul_f32 v[4:5], v[156:157], v[4:5]
	v_pk_mul_f32 v[6:7], v[158:159], v[6:7]
	s_waitcnt vmcnt(10)
	v_pk_add_f32 v[8:9], v[162:163], 1.0 op_sel_hi:[1,0]
	v_pk_add_f32 v[10:11], v[160:161], 1.0 op_sel_hi:[1,0]
	s_waitcnt vmcnt(9)
	v_pk_fma_f32 v[6:7], v[8:9], v[6:7], v[166:167]
	v_pk_fma_f32 v[4:5], v[10:11], v[4:5], v[164:165]
	s_nop 0
	v_cvt_pk_bf16_f32 v4, v4, v5
	v_cvt_pk_bf16_f32 v5, v6, v7
	global_store_dwordx2 v[72:73], v[4:5], off offset:3072
	s_nop 0
	s_waitcnt vmcnt(9)
	v_pk_mul_f32 v[0:1], v[168:169], v[0:1]
	v_pk_mul_f32 v[2:3], v[170:171], v[2:3]
	s_waitcnt vmcnt(8)
	v_pk_add_f32 v[4:5], v[174:175], 1.0 op_sel_hi:[1,0]
	v_pk_add_f32 v[6:7], v[172:173], 1.0 op_sel_hi:[1,0]
	s_waitcnt vmcnt(7)
	v_pk_fma_f32 v[2:3], v[4:5], v[2:3], v[178:179]
	v_pk_fma_f32 v[0:1], v[6:7], v[0:1], v[176:177]
	s_nop 0
	v_cvt_pk_bf16_f32 v0, v0, v1
	v_cvt_pk_bf16_f32 v1, v2, v3
	global_store_dwordx2 v[72:73], v[0:1], off offset:3584
	s_cbranch_scc1 .LBB0_166
